# v22: v21 + every workgroup runs its prompt tile of the output projection in the sample-combine phase (the output-projection phase keeps only the sample slices); the attention-phase order split uses bi
# baseline (speedup 1.0000x reference)
.LBB0_1308:
	s_bitcmp1_b32 s94, 3
	s_cbranch_scc1 .Lattn_first
	s_cmpk_lt_i32 s94, 0x400
	s_cbranch_scc1 .LBB0_1310

.LBB0_1312:
	s_mov_b64 s[22:23], s[4:5]
	s_mov_b64 s[18:19], s[64:65]
	s_mov_b64 s[20:21], s[2:3]
	s_mov_b64 s[28:29], s[6:7]
	s_mov_b64 s[24:25], s[8:9]
	s_mov_b64 s[30:31], s[0:1]
	s_ashr_i32 s26, s54, 9
	v_lshl_add_u64 v[2:3], s[28:29], 0, v[34:35]
	v_lshl_add_u64 v[2:3], v[2:3], 0, s[14:15]
	flat_load_dwordx4 v[16:19], v[2:3]
	v_readfirstlane_b32 s12, v52
	s_ashr_i32 s27, s26, 31
	s_ashr_i32 s55, s12, 3
	s_and_b32 s57, s38, 0xfc0
	s_lshl_b64 s[26:27], s[26:27], 12
	s_andn2_b32 s55, s55, 31
	v_lshl_add_u64 v[4:5], s[28:29], 0, v[32:33]
	v_lshl_add_u64 v[6:7], s[28:29], 0, v[30:31]
	v_lshl_add_u64 v[8:9], s[28:29], 0, v[28:29]
	s_or_b32 s26, s26, s57
	s_ashr_i32 s29, s55, 31
	v_mov_b64_e32 v[0:1], s[30:31]
	v_lshl_add_u64 v[46:47], v[4:5], 0, s[14:15]
	s_add_u32 s28, s26, s55
	v_lshl_add_u64 v[4:5], s[26:27], 0, v[26:27]
	s_addc_u32 s29, s27, s29
	v_mad_u64_u32 v[0:1], s[26:27], v4, s36, v[0:1]
	v_lshl_add_u64 v[44:45], v[6:7], 0, s[14:15]
	v_or_b32_e32 v6, s55, v54
	s_lshl_b64 s[26:27], s[28:29], 12
	v_lshl_add_u64 v[42:43], v[8:9], 0, s[14:15]
	v_mul_lo_u32 v8, v6, s37
	v_lshlrev_b64 v[6:7], 11, v[4:5]
	s_add_u32 s22, s22, s26
	v_or_b32_e32 v2, s28, v20
	v_mov_b32_e32 v3, s29
	v_mad_i32_i24 v1, v5, s36, v1
	v_lshl_add_u64 v[4:5], s[24:25], 0, v[6:7]
	s_addc_u32 s23, s23, s27
	s_and_b32 s24, s10, 0x380
	v_lshlrev_b64 v[2:3], 11, v[2:3]
	s_lshl_b32 s25, s24, 2
	v_lshl_add_u64 v[2:3], s[20:21], 0, v[2:3]
	s_add_u32 s20, s22, s25
	s_addc_u32 s21, s23, 0
	s_lshr_b32 s12, s12, 1
	s_and_b32 s12, s12, 0x60
	s_lshl_b32 s22, s12, 2
	s_add_u32 s20, s20, s22
	s_addc_u32 s21, s21, 0
	v_lshl_add_u32 v65, s12, 1, v53
	s_lshl_b32 s12, s24, 1
	v_lshl_add_u64 v[6:7], s[20:21], 0, v[36:37]
	v_lshl_add_u64 v[4:5], v[4:5], 0, s[12:13]
	v_lshl_add_u64 v[6:7], v[6:7], 0, v[24:25]
	v_lshl_add_u64 v[48:49], v[4:5], 0, v[40:41]
	v_add_co_u32_e32 v4, vcc, s33, v6
	v_add3_u32 v131, v55, s22, v8
	s_nop 0
	v_addc_co_u32_e32 v5, vcc, 0, v7, vcc
	v_add_co_u32_e32 v8, vcc, s34, v6
	v_lshl_add_u64 v[2:3], v[2:3], 0, s[12:13]
	s_nop 0
	v_addc_co_u32_e32 v9, vcc, 0, v7, vcc
	v_add_co_u32_e32 v10, vcc, s35, v6
	v_lshl_add_u64 v[0:1], v[0:1], 0, s[12:13]
	s_nop 0
	v_addc_co_u32_e32 v11, vcc, 0, v7, vcc
	v_add_co_u32_e32 v12, vcc, s41, v6
	s_add_u32 s18, s18, s25
	s_nop 0
	v_addc_co_u32_e32 v13, vcc, 0, v7, vcc
	v_add_co_u32_e32 v14, vcc, s42, v6
	v_lshl_add_u64 v[2:3], v[2:3], 0, v[38:39]
	s_nop 0
	v_addc_co_u32_e32 v15, vcc, 0, v7, vcc
	v_add_co_u32_e32 v106, vcc, s43, v6
	v_lshl_add_u64 v[0:1], v[0:1], 0, v[40:41]
	s_nop 0
	v_addc_co_u32_e32 v107, vcc, 0, v7, vcc
	v_add_co_u32_e32 v108, vcc, s44, v6
	s_addc_u32 s19, s19, 0
	s_nop 0
	v_addc_co_u32_e32 v109, vcc, 0, v7, vcc
	v_add_co_u32_e32 v110, vcc, s45, v6
	flat_load_dwordx4 v[66:69], v[2:3]
	flat_load_dwordx4 v[70:73], v[2:3] offset:32
	flat_load_dwordx4 v[74:77], v[2:3] offset:64
	flat_load_dwordx4 v[78:81], v[2:3] offset:96
	flat_load_dwordx4 v[82:85], v[2:3] offset:128
	flat_load_dwordx4 v[86:89], v[2:3] offset:160
	flat_load_dwordx4 v[90:93], v[2:3] offset:192
	flat_load_dwordx4 v[94:97], v[2:3] offset:224
	flat_load_dwordx4 v[98:101], v[0:1]
	flat_load_dwordx4 v[102:105], v[0:1] offset:16
	v_addc_co_u32_e32 v111, vcc, 0, v7, vcc
	v_add_co_u32_e32 v112, vcc, s46, v6
	v_lshl_add_u64 v[126:127], s[18:19], 0, v[22:23]
	s_nop 0
	v_addc_co_u32_e32 v113, vcc, 0, v7, vcc
	v_add_co_u32_e32 v114, vcc, s47, v6
	v_add_u32_e32 v130, 0xa000, v65
	s_nop 0
	v_addc_co_u32_e32 v115, vcc, 0, v7, vcc
	v_add_co_u32_e32 v116, vcc, s48, v6
	v_add_u32_e32 v132, 0x400, v131
	s_nop 0
	v_addc_co_u32_e32 v117, vcc, 0, v7, vcc
	v_add_co_u32_e32 v118, vcc, s49, v6
	v_add_u32_e32 v133, 0x1000, v131
	s_nop 0
	v_addc_co_u32_e32 v119, vcc, 0, v7, vcc
	v_add_co_u32_e32 v120, vcc, s50, v6
	v_add_u32_e32 v134, 0x1400, v131
	s_nop 0
	v_addc_co_u32_e32 v121, vcc, 0, v7, vcc
	v_add_co_u32_e32 v122, vcc, s51, v6
	v_add_u32_e32 v135, 0x2000, v131
	s_nop 0
	v_addc_co_u32_e32 v123, vcc, 0, v7, vcc
	v_add_co_u32_e32 v124, vcc, s52, v6
	v_add_u32_e32 v136, 0x2400, v131
	s_nop 0
	v_addc_co_u32_e32 v125, vcc, 0, v7, vcc
	flat_load_dword v0, v[6:7]
	flat_load_dword v1, v[4:5]
	flat_load_dword v2, v[8:9]
	flat_load_dword v3, v[10:11]
	s_nop 0
	flat_load_dword v4, v[12:13]
	flat_load_dword v5, v[14:15]
	flat_load_dword v6, v[106:107]
	flat_load_dword v7, v[108:109]
	flat_load_dword v8, v[110:111]
	flat_load_dword v9, v[112:113]
	flat_load_dword v10, v[114:115]
	flat_load_dword v11, v[116:117]
	flat_load_dword v12, v[118:119]
	flat_load_dword v13, v[120:121]
	flat_load_dword v14, v[122:123]
	flat_load_dword v15, v[124:125]
	flat_load_dwordx4 v[106:109], v[126:127]
	flat_load_dwordx4 v[110:113], v[126:127] offset:16
	flat_load_dwordx4 v[114:117], v[126:127] offset:32
	flat_load_dwordx4 v[118:121], v[126:127] offset:48
	flat_load_dwordx4 v[240:243], v[46:47]
	flat_load_dwordx4 v[244:247], v[44:45]
	flat_load_dwordx4 v[248:251], v[42:43]
	s_waitcnt vmcnt(0) lgkmcnt(0)
	ds_write_b128 v60, v[16:19] offset:40960
	ds_write_b128 v61, v[240:243] offset:40960
	ds_write_b128 v62, v[244:247] offset:40960
	ds_write_b128 v63, v[248:251] offset:40960
	v_add_u32_e32 v137, 0x3000, v131
	v_add_u32_e32 v138, 0x3400, v131
	s_add_i32 s54, s54, s92
	s_add_i32 s38, s38, s39
	s_add_i32 s10, s10, s40
	s_add_u32 s14, s14, s16
	s_addc_u32 s15, s15, s17
	s_cmpk_gt_i32 s54, 0x3ff
	v_and_b32_e32 v125, 0xffff0000, v101
	v_and_b32_e32 v47, 0xffff0000, v104
	v_lshlrev_b32_e32 v46, 16, v104
	v_and_b32_e32 v129, 0xffff0000, v105
	v_lshlrev_b32_e32 v128, 16, v105
	v_lshlrev_b32_e32 v124, 16, v101
	v_and_b32_e32 v101, 0xffff0000, v100
	v_lshlrev_b32_e32 v100, 16, v100
	v_and_b32_e32 v127, 0xffff0000, v99
	v_lshlrev_b32_e32 v126, 16, v99
	v_and_b32_e32 v99, 0xffff0000, v98
	v_lshlrev_b32_e32 v98, 16, v98
	v_and_b32_e32 v123, 0xffff0000, v103
	v_lshlrev_b32_e32 v122, 16, v103
	v_and_b32_e32 v103, 0xffff0000, v102
	v_lshlrev_b32_e32 v102, 16, v102
	s_waitcnt vmcnt(0) lgkmcnt(0)
	s_barrier
	ds_read_u16 v16, v65 offset:40960
	ds_read_u16 v17, v65 offset:41232
	ds_read_u16 v18, v65 offset:41504
	ds_read_u16 v19, v65 offset:41776
	ds_read_u16 v42, v65 offset:42048
	ds_read_u16 v43, v65 offset:42320
	ds_read_u16 v44, v65 offset:42592
	ds_read_u16 v45, v65 offset:42864
	ds_read_u16 v104, v65 offset:45312
	ds_read_u16 v105, v65 offset:45584
	ds_read_u16 v139, v65 offset:45856
	ds_read_u16 v140, v65 offset:46128
	ds_read_u16 v141, v65 offset:46400
	ds_read_u16 v142, v65 offset:46672
	ds_read_u16 v143, v65 offset:46944
	ds_read_u16 v144, v65 offset:47216
	ds_read_u16 v145, v65 offset:49664
	ds_read_u16 v146, v65 offset:49936
	ds_read_u16 v147, v65 offset:50208
	ds_read_u16 v148, v65 offset:50480
	ds_read_u16 v149, v65 offset:50752
	ds_read_u16 v150, v65 offset:51024
	ds_read_u16 v151, v65 offset:51296
	ds_read_u16 v152, v65 offset:51568
	ds_read_u16 v153, v65 offset:54016
	ds_read_u16 v154, v65 offset:54288
	ds_read_u16 v155, v65 offset:54560
	ds_read_u16 v156, v65 offset:54832
	ds_read_u16 v157, v65 offset:55104
	ds_read_u16 v158, v65 offset:55376
	ds_read_u16 v159, v65 offset:55648
	ds_read_u16 v160, v65 offset:55920
	ds_read_u16 v161, v65 offset:58368
	ds_read_u16 v162, v65 offset:58640
	ds_read_u16 v163, v65 offset:58912
	ds_read_u16 v164, v65 offset:59184
	ds_read_u16 v165, v65 offset:59456
	ds_read_u16 v166, v65 offset:59728
	ds_read_u16 v167, v65 offset:60000
	ds_read_u16 v168, v65 offset:60272
	ds_read_u16 v169, v65 offset:62720
	ds_read_u16 v170, v65 offset:62992
	ds_read_u16 v171, v65 offset:63264
	ds_read_u16 v172, v65 offset:63536
	s_waitcnt lgkmcnt(14)
	v_lshl_or_b32 v16, v17, 16, v16
	v_lshl_or_b32 v17, v19, 16, v18
	v_lshl_or_b32 v18, v43, 16, v42
	v_lshl_or_b32 v19, v45, 16, v44
	ds_read_u16 v42, v65 offset:63808
	ds_read_u16 v43, v65 offset:64080
	ds_read_u16 v44, v65 offset:64352
	v_mfma_f32_32x32x16_bf16 v[0:15], v[66:69], v[16:19], v[0:15]
	v_lshl_or_b32 v16, v105, 16, v104
	v_lshl_or_b32 v17, v140, 16, v139
	v_lshl_or_b32 v18, v142, 16, v141
	v_lshl_or_b32 v19, v144, 16, v143
	ds_read_u16 v45, v65 offset:64624
	ds_read_u16 v65, v130 offset:26112
	ds_read_u16 v66, v130 offset:26384
	ds_read_u16 v67, v130 offset:26656
	ds_read_u16 v68, v130 offset:26928
	ds_read_u16 v69, v130 offset:27200
	v_mfma_f32_32x32x16_bf16 v[0:15], v[70:73], v[16:19], v[0:15]
	v_lshl_or_b32 v16, v146, 16, v145
	v_lshl_or_b32 v17, v148, 16, v147
	v_lshl_or_b32 v18, v150, 16, v149
	v_lshl_or_b32 v19, v152, 16, v151
	ds_read_u16 v70, v130 offset:27472
	ds_read_u16 v71, v130 offset:27744
	ds_read_u16 v72, v130 offset:28016
	v_mfma_f32_32x32x16_bf16 v[0:15], v[74:77], v[16:19], v[0:15]
	v_lshl_or_b32 v16, v154, 16, v153
	v_lshl_or_b32 v17, v156, 16, v155
	v_lshl_or_b32 v18, v158, 16, v157
	s_waitcnt lgkmcnt(14)
	v_lshl_or_b32 v19, v160, 16, v159
	ds_read_u16 v73, v130 offset:30464
	ds_read_u16 v74, v130 offset:30736
	ds_read_u16 v75, v130 offset:31008
	v_mfma_f32_32x32x16_bf16 v[0:15], v[78:81], v[16:19], v[0:15]
	v_lshl_or_b32 v16, v162, 16, v161
	v_lshl_or_b32 v17, v164, 16, v163
	v_lshl_or_b32 v18, v166, 16, v165
	v_lshl_or_b32 v19, v168, 16, v167
	s_nop 1
	v_mfma_f32_32x32x16_bf16 v[0:15], v[82:85], v[16:19], v[0:15]
	v_lshl_or_b32 v16, v170, 16, v169
	s_waitcnt lgkmcnt(14)
	v_lshl_or_b32 v17, v172, 16, v171
	s_waitcnt lgkmcnt(13)
	v_lshl_or_b32 v18, v43, 16, v42
	s_waitcnt lgkmcnt(11)
	v_lshl_or_b32 v19, v45, 16, v44
	ds_read_u16 v42, v130 offset:31280
	ds_read_u16 v43, v130 offset:31552
	ds_read_u16 v44, v130 offset:31824
	v_mfma_f32_32x32x16_bf16 v[0:15], v[86:89], v[16:19], v[0:15]
	s_waitcnt lgkmcnt(12)
	v_lshl_or_b32 v16, v66, 16, v65
	s_waitcnt lgkmcnt(10)
	v_lshl_or_b32 v17, v68, 16, v67
	s_waitcnt lgkmcnt(8)
	v_lshl_or_b32 v18, v70, 16, v69
	s_waitcnt lgkmcnt(6)
	v_lshl_or_b32 v19, v72, 16, v71
	s_nop 1
	v_mfma_f32_32x32x16_bf16 v[0:15], v[90:93], v[16:19], v[0:15]
	ds_read_u16 v19, v130 offset:32096
	ds_read_u16 v45, v130 offset:32368
	s_waitcnt lgkmcnt(6)
	v_lshl_or_b32 v16, v74, 16, v73
	s_waitcnt lgkmcnt(4)
	v_lshl_or_b32 v17, v42, 16, v75
	s_waitcnt lgkmcnt(2)
	v_lshl_or_b32 v18, v44, 16, v43
	s_waitcnt lgkmcnt(0)
	v_lshl_or_b32 v19, v45, 16, v19
	s_nop 1
	v_mfma_f32_32x32x16_bf16 v[0:15], v[94:97], v[16:19], v[0:15]
	s_nop 11
	ds_write2_b32 v131, v0, v1 offset1:132
	ds_write2_b32 v132, v2, v3 offset0:8 offset1:140
	ds_write2_b32 v133, v4, v5 offset0:32 offset1:164
	ds_write2_b32 v134, v6, v7 offset0:40 offset1:172
	ds_write2_b32 v135, v8, v9 offset0:64 offset1:196
	ds_write2_b32 v136, v10, v11 offset0:72 offset1:204
	ds_write2_b32 v137, v12, v13 offset0:96 offset1:228
	ds_write2_b32 v138, v14, v15 offset0:104 offset1:236
	s_waitcnt lgkmcnt(0)
	s_barrier
	ds_read_b128 v[0:3], v56 offset:48
	ds_read_b128 v[4:7], v56 offset:32
	ds_read_b128 v[8:11], v56
	ds_read_b128 v[12:15], v56 offset:16
	s_waitcnt lgkmcnt(3)
	v_pk_mul_f32 v[18:19], v[0:1], v[0:1]
	s_waitcnt lgkmcnt(2)
	v_pk_mul_f32 v[44:45], v[4:5], v[4:5]
	s_waitcnt lgkmcnt(1)
	v_pk_mul_f32 v[72:73], v[8:9], v[8:9]
	v_pk_mul_f32 v[70:71], v[10:11], v[10:11]
	v_add_f32_e32 v65, v72, v73
	v_add_f32_e32 v65, v65, v70
	s_waitcnt lgkmcnt(0)
	v_pk_mul_f32 v[68:69], v[12:13], v[12:13]
	v_add_f32_e32 v65, v65, v71
	v_add_f32_e32 v65, v65, v68
	v_pk_mul_f32 v[66:67], v[14:15], v[14:15]
	v_add_f32_e32 v65, v65, v69
	v_add_f32_e32 v65, v65, v66
	v_add_f32_e32 v65, v65, v67
	v_add_f32_e32 v44, v65, v44
	v_pk_mul_f32 v[42:43], v[6:7], v[6:7]
	v_add_f32_e32 v44, v44, v45
	v_add_f32_e32 v42, v44, v42
	v_add_f32_e32 v42, v42, v43
	v_add_f32_e32 v18, v42, v18
	v_pk_mul_f32 v[16:17], v[2:3], v[2:3]
	v_add_f32_e32 v18, v18, v19
	v_add_f32_e32 v16, v18, v16
	v_add_f32_e32 v16, v16, v17
	ds_bpermute_b32 v17, v57, v16
	s_waitcnt lgkmcnt(0)
	v_add_f32_e32 v16, v16, v17
	ds_bpermute_b32 v17, v58, v16
	s_waitcnt lgkmcnt(0)
	v_add_f32_e32 v16, v16, v17
	ds_bpermute_b32 v17, v59, v16
	s_waitcnt lgkmcnt(0)
	v_add_f32_e32 v16, v16, v17
	v_fmamk_f32 v16, v16, 0x3c000000, v64
	v_mul_f32_e32 v17, 0x4b800000, v16
	v_cmp_gt_f32_e32 vcc, s53, v16
	s_nop 1
	v_cndmask_b32_e32 v16, v16, v17, vcc
	v_rsq_f32_e32 v16, v16
	s_nop 0
	v_mul_f32_e32 v17, 0x45800000, v16
	v_cndmask_b32_e32 v16, v16, v17, vcc
	v_pk_mul_f32 v[8:9], v[8:9], v[16:17] op_sel_hi:[1,0]
	v_pk_mul_f32 v[10:11], v[10:11], v[16:17] op_sel_hi:[1,0]
	v_pk_mul_f32 v[12:13], v[12:13], v[16:17] op_sel_hi:[1,0]
	v_pk_mul_f32 v[14:15], v[14:15], v[16:17] op_sel_hi:[1,0]
	v_pk_mul_f32 v[4:5], v[4:5], v[16:17] op_sel_hi:[1,0]
	v_pk_mul_f32 v[6:7], v[6:7], v[16:17] op_sel_hi:[1,0]
	v_pk_mul_f32 v[0:1], v[0:1], v[16:17] op_sel_hi:[1,0]
	v_pk_mul_f32 v[2:3], v[2:3], v[16:17] op_sel_hi:[1,0]
	v_pk_mul_f32 v[8:9], v[106:107], v[8:9]
	v_pk_mul_f32 v[10:11], v[108:109], v[10:11]
	v_pk_mul_f32 v[12:13], v[110:111], v[12:13]
	v_pk_mul_f32 v[14:15], v[112:113], v[14:15]
	v_pk_mul_f32 v[4:5], v[114:115], v[4:5]
	v_pk_mul_f32 v[6:7], v[116:117], v[6:7]
	v_pk_mul_f32 v[0:1], v[118:119], v[0:1]
	v_pk_mul_f32 v[2:3], v[120:121], v[2:3]
	v_pk_mul_f32 v[8:9], v[8:9], v[98:99]
	v_pk_mul_f32 v[10:11], v[10:11], v[126:127]
	v_pk_mul_f32 v[12:13], v[12:13], v[100:101]
	v_pk_mul_f32 v[14:15], v[14:15], v[124:125]
	v_pk_mul_f32 v[4:5], v[4:5], v[102:103]
	v_pk_mul_f32 v[6:7], v[6:7], v[122:123]
	v_pk_mul_f32 v[16:17], v[0:1], v[46:47]
	v_pk_mul_f32 v[18:19], v[2:3], v[128:129]
	v_cvt_pk_bf16_f32 v0, v8, v9
	v_cvt_pk_bf16_f32 v1, v10, v11
	v_cvt_pk_bf16_f32 v2, v12, v13
	v_cvt_pk_bf16_f32 v3, v14, v15
	v_cvt_pk_bf16_f32 v4, v4, v5
	v_cvt_pk_bf16_f32 v5, v6, v7
	v_cvt_pk_bf16_f32 v6, v16, v17
	v_cvt_pk_bf16_f32 v7, v18, v19
	flat_store_dwordx4 v[48:49], v[0:3]
	flat_store_dwordx4 v[48:49], v[4:7] offset:16
	s_waitcnt lgkmcnt(0)
	s_barrier
	s_cbranch_scc0 .LBB0_1312
	v_mov_b32_e32 v217, s11
	s_bitcmp1_b32 s94, 3
	s_cbranch_scc1 .Lattn_done

.LBB0_1595:
	v_readlane_b32 s96, v238, 5
	v_readlane_b32 s64, v239, 51
	v_readlane_b32 s2, v238, 48
	v_readlane_b32 s92, v238, 38
	v_readlane_b32 s94, v238, 40
	v_readlane_b32 s87, v238, 4
	v_readlane_b32 s97, v238, 6
	v_readlane_b32 s84, v238, 7
	v_readlane_b32 s65, v239, 52
	v_readlane_b32 s68, v239, 55
	v_readlane_b32 s69, v239, 56
	v_readlane_b32 s76, v239, 63
	v_readlane_b32 s77, v238, 0
	v_readlane_b32 s3, v238, 49
	v_readlane_b32 s93, v238, 39
	v_readlane_b32 s95, v238, 41
	v_readlane_b32 s66, v239, 53
	v_readlane_b32 s67, v239, 54
	v_readlane_b32 s70, v239, 57
	v_readlane_b32 s71, v239, 58
	v_readlane_b32 s72, v239, 59
	v_readlane_b32 s73, v239, 60
	v_readlane_b32 s74, v239, 61
	v_readlane_b32 s75, v239, 62
	v_readlane_b32 s78, v238, 1
	v_readlane_b32 s79, v238, 2
	s_bitcmp1_b32 s94, 3
	s_cbranch_scc0 .LBB0_1596
	s_lshl_b32 s10, s94, 1
	s_branch .LBB0_1310

.LBB0_2057:
	s_cmp_lt_i32 s96, 9
	s_cselect_b64 s[2:3], -1, 0
	s_and_b64 s[0:1], s[2:3], s[0:1]
	s_andn2_b64 vcc, exec, s[0:1]
	s_cbranch_vccnz .LBB0_2061
	s_mov_b32 s98, 0
	s_branch .Lout_body
.Lout_ret:
	s_cmp_lt_i32 s96, 9
	s_cselect_b64 s[2:3], -1, 0
	v_readlane_b32 s76, v239, 63
	v_readlane_b32 s77, v238, 0
	s_lshl_b32 s0, s94, 3
	v_readlane_b32 s1, v238, 3
	s_add_i32 s30, s1, s0
	s_cmpk_gt_i32 s30, 0x7ff
	s_cbranch_scc1 .LBB0_2061
	s_add_u32 s31, s90, 0x44c71600
	s_addc_u32 s33, s91, 0
	s_bfe_u32 s0, s87, 0x30006
	s_lshl_b32 s34, s92, 3
	s_bfe_u32 s35, s87, 0x20006
	s_mul_i32 s1, s0, 12
	s_add_u32 s1, s90, s1
	s_addc_u32 s4, s91, 0
	s_add_u32 s36, s1, 0x25c2b600
	s_addc_u32 s37, s4, 0
	s_lshl_b32 s0, s0, 8
	s_waitcnt vmcnt(0)
	v_mbcnt_hi_u32_b32 v4, -1, v216
	s_add_u32 s0, s90, s0
	v_mov_b32_e32 v1, 0
	s_addc_u32 s1, s91, 0
	v_lshlrev_b32_e32 v0, 1, v4
	v_lshl_add_u64 v[2:3], s[0:1], 0, v[0:1]
	s_mov_b64 s[0:1], 0x102ab600
	v_lshl_add_u64 v[2:3], v[2:3], 0, s[0:1]
	v_lshlrev_b32_e32 v0, 2, v4
	v_mov_b32_e32 v4, 0xc000
	s_mov_b64 s[6:7], 0xc600
	s_mov_b32 s38, 0xc000
	v_mov_b32_e32 v5, 0x18000
	s_mov_b64 s[8:9], 0x18c00
	s_mov_b32 s39, 0x18000
	v_mov_b32_e32 v6, 0x25000
	s_mov_b64 s[10:11], 0x25200
	s_mov_b32 s40, 0x25000
	v_mov_b32_e32 v7, 0x4000
	s_mov_b64 s[12:13], 0x4200
	s_movk_i32 s41, 0x4000
	v_mov_b32_e32 v8, 0x10000
	s_mov_b64 s[14:15], 0x10800
	s_mov_b32 s42, 0x10000
	v_mov_b32_e32 v9, 0x1d000
	s_mov_b64 s[16:17], 0x1ce00
	s_mov_b32 s43, 0x1c000
	v_mov_b32_e32 v10, 0x29000
	s_mov_b64 s[18:19], 0x29400
	s_mov_b32 s44, 0x29000
	v_mov_b32_e32 v11, 0x8000
	s_mov_b64 s[20:21], 0x8400
	s_mov_b32 s45, 0x8000
	v_mov_b32_e32 v12, 0x14000
	s_mov_b64 s[22:23], 0x14a00
	s_mov_b32 s46, 0x14000
	v_mov_b32_e32 v13, 0x21000
	s_mov_b64 s[24:25], 0x21000
	s_mov_b32 s47, 0x21000
	v_mov_b32_e32 v14, 0x2d000
	s_mov_b64 s[26:27], 0x2d600
	s_mov_b32 s48, 0x2d000
	s_movk_i32 s49, 0x7fff

.LBB0_2348:
	s_cmp_lt_i32 s96, 12
	s_cselect_b64 s[2:3], -1, 0
	s_and_b64 s[0:1], s[2:3], s[0:1]
	s_andn2_b64 vcc, exec, s[0:1]
	s_cbranch_vccnz .LBB0_2375
	s_mov_b32 s98, 1
	s_cmp_gt_i32 s94, 63
	s_cbranch_scc1 .LBB0_2375
.Lout_body:
	s_lshl_b32 s4, s98, 8
	s_sub_i32 s4, 0x100, s4
	s_add_i32 s4, s4, s94
	s_cmp_lt_i32 s4, 64
	s_cselect_b64 s[0:1], -1, 0
	s_cmp_gt_i32 s4, 63
	s_cbranch_scc0 .LBB0_2354
	s_mov_b64 s[10:11], 0
	s_cmpk_lt_u32 s94, 0x100
	s_mov_b64 s[8:9], 0
	s_cbranch_scc0 .LBB0_2352
	s_lshl_b32 s5, s94, 5
	s_lshr_b32 s4, s94, 3
	s_lshl_b32 s6, s94, 2
	s_and_b32 s5, s5, 32
	s_and_b32 s6, s6, 24
	s_or_b32 s4, s5, s4
	s_bfe_u32 s5, s94, 0x30003
	s_or_b32 s6, s5, s6
	s_lshr_b32 s4, s4, 3
	s_mov_b64 s[8:9], -1

.LBB0_2360:
	s_add_i32 s7, s7, 1
	s_add_i32 s0, s7, s52
	s_add_i32 s0, s0, s98
	s_mul_hi_i32 s1, s0, s92
	s_mul_i32 s0, s0, s92
	s_add_u32 s24, s0, s94
	s_addc_u32 s25, s1, s53
	v_cmp_gt_i64_e64 s[0:1], s[24:25], v[140:141]
	s_and_b64 vcc, exec, s[0:1]
	s_cbranch_vccnz .LBB0_2366
	s_ashr_i32 s5, s24, 31
	s_lshr_b32 s5, s5, 29
	s_add_i32 s5, s24, s5
	s_and_b32 s20, s5, -8
	s_sub_i32 s22, s24, s20
	s_cmp_gt_i32 s22, -1
	s_mov_b64 s[20:21], -1
	s_cbranch_scc0 .LBB0_2363
	s_lshl_b32 s23, s22, 5
	s_mov_b64 s[20:21], 0

.LBB0_2374:
	s_barrier
	s_cmp_eq_u32 s98, 0
	s_cbranch_scc1 .Lout_ret

	.amdhsa_kernel _Z6mk_fwd4Args
		.amdhsa_group_segment_fixed_size 0
		.amdhsa_private_segment_fixed_size 0
		.amdhsa_kernarg_size 536
		.amdhsa_user_sgpr_count 2
		.amdhsa_user_sgpr_dispatch_ptr 0
		.amdhsa_user_sgpr_queue_ptr 0
		.amdhsa_user_sgpr_kernarg_segment_ptr 1
		.amdhsa_user_sgpr_dispatch_id 0
		.amdhsa_user_sgpr_kernarg_preload_length 0
		.amdhsa_user_sgpr_kernarg_preload_offset 0
		.amdhsa_user_sgpr_private_segment_size 0
		.amdhsa_uses_dynamic_stack 0
		.amdhsa_enable_private_segment 0
		.amdhsa_system_sgpr_workgroup_id_x 1
		.amdhsa_system_sgpr_workgroup_id_y 0
		.amdhsa_system_sgpr_workgroup_id_z 0
		.amdhsa_system_sgpr_workgroup_info 0
		.amdhsa_system_vgpr_workitem_id 0
		.amdhsa_next_free_vgpr 256
		.amdhsa_next_free_sgpr 102
		.amdhsa_accum_offset 256
		.amdhsa_reserve_vcc 1
		.amdhsa_float_round_mode_32 0
		.amdhsa_float_round_mode_16_64 0
		.amdhsa_float_denorm_mode_32 3
		.amdhsa_float_denorm_mode_16_64 3
		.amdhsa_dx10_clamp 1
		.amdhsa_ieee_mode 1
		.amdhsa_fp16_overflow 0
		.amdhsa_tg_split 0
		.amdhsa_exception_fp_ieee_invalid_op 0
		.amdhsa_exception_fp_denorm_src 0
		.amdhsa_exception_fp_ieee_div_zero 0
		.amdhsa_exception_fp_ieee_overflow 0
		.amdhsa_exception_fp_ieee_underflow 0
		.amdhsa_exception_fp_ieee_inexact 0
		.amdhsa_exception_int_div_zero 0
	.end_amdhsa_kernel

amdhsa.kernels:
  - .agpr_count:     0
    .args:
      - .offset:         0
        .size:           280
        .value_kind:     by_value
      - .offset:         280
        .size:           4
        .value_kind:     hidden_block_count_x
      - .offset:         284
        .size:           4
        .value_kind:     hidden_block_count_y
      - .offset:         288
        .size:           4
        .value_kind:     hidden_block_count_z
      - .offset:         292
        .size:           2
        .value_kind:     hidden_group_size_x
      - .offset:         294
        .size:           2
        .value_kind:     hidden_group_size_y
      - .offset:         296
        .size:           2
        .value_kind:     hidden_group_size_z
      - .offset:         298
        .size:           2
        .value_kind:     hidden_remainder_x
      - .offset:         300
        .size:           2
        .value_kind:     hidden_remainder_y
      - .offset:         302
        .size:           2
        .value_kind:     hidden_remainder_z
      - .offset:         320
        .size:           8
        .value_kind:     hidden_global_offset_x
      - .offset:         328
        .size:           8
        .value_kind:     hidden_global_offset_y
      - .offset:         336
        .size:           8
        .value_kind:     hidden_global_offset_z
      - .offset:         344
        .size:           2
        .value_kind:     hidden_grid_dims
      - .offset:         400
        .size:           4
        .value_kind:     hidden_dynamic_lds_size
    .group_segment_fixed_size: 0
    .kernarg_segment_align: 8
    .kernarg_segment_size: 536
    .language:       OpenCL C
    .language_version:
      - 2
      - 0
    .max_flat_workgroup_size: 512
    .name:           _Z6mk_fwd4Args
    .private_segment_fixed_size: 0
    .sgpr_count:     108
    .sgpr_spill_count: 209
    .symbol:         _Z6mk_fwd4Args.kd
    .uniform_work_group_size: 1
    .uses_dynamic_stack: false
    .vgpr_count:     256
    .vgpr_spill_count: 0
    .wavefront_size: 64
